# v15 plus phase-head kernarg loads issued together under one wait
# speedup vs baseline: 1.0061x; 1.0017x over previous
; #define GAS __attribute__((address_space(1)))
; #define KIND_IS(x) ([&]() { int kd_ = d.kind; asm volatile("" : "+s"(kd_)); return kd_ == (x); }())
; __device__ __forceinline__ void norm_rows_f32_inplace(float* x, const float* gain, int nrows, int gw, int NGW, int lane) {
;     f32x4 g[4];
; #pragma unroll
;     for (int j = 0; j < 4; ++j) g[j] = *((const f32x4*)gain + lane + 64 * j);
;     for (int m = gw * 4; m < nrows; m += NGW * 4) {
;         GAS f32x4* xr = (GAS f32x4*)(x + (size_t)m * D) + lane;
; __global__ void __launch_bounds__(NWAVES * 64, 2) fwd_megakernel(Args args) {
;     ...
;         const int ck = ph / PPC, idx = ph - ck * PPC;
;         const Ph& d = args.tab[idx];
;         const int tok0 = ck * CH, grp = tok0 / GROUP_TOK, seq_len = grp ? 4096 : 2048;
;         const float* xin = args.p.x_in[grp] + (size_t)(tok0 - grp * GROUP_TOK) * D;
;         float* X = args.p.out + (size_t)tok0 * D;
;         const void* A = (d.flags & F_A_IN) ? (const void*)xin : d.A;
;         const void* aux = (d.flags & F_AUX_IN) ? (const void*)xin : d.aux;
;     ...
;         if (0) {}
;         else if (KIND_IS(K_POOL)) { { int tid2 = threadIdx.x; asm volatile("" : "+v"(tid2));
;             if (d.flags & F_B16) pool_phase<true>(lds, nullptr, (const bf16*)d.A, d.st, (const float*)aux, (bf16*)d.C, seq_len, vcu, G, tid2, __builtin_amdgcn_readfirstlane(tid2 >> 6), tid2 & 63);
;             else pool_phase<false>(lds, (const float*)A, nullptr, nullptr, (const float*)aux, (bf16*)d.C, seq_len, vcu, G, tid2, __builtin_amdgcn_readfirstlane(tid2 >> 6), tid2 & 63); } }
.LBB0_67:
	s_and_b32 s0, s88, 0xff
	s_mul_i32 s0, s0, 27
	s_lshr_b32 s36, s0, 9
	s_mul_i32 s0, s36, 0xffffffed
	s_add_i32 s0, s0, s88
	s_mul_hi_i32 s1, s0, 0x50
	s_mulk_i32 s0, 0x50
	s_add_u32 s14, s74, s0
	s_addc_u32 s15, s75, s1
	s_lshl_b32 s4, s36, 15
	s_cmp_gt_u32 s88, 37
	s_cselect_b64 s[0:1], -1, 0
	s_waitcnt vmcnt(0)
	v_cndmask_b32_e64 v0, 0, 1, s[0:1]
	s_and_b64 s[0:1], s[0:1], exec
	v_readfirstlane_b32 s0, v0
	s_cselect_b32 s5, 0xffff0000, 0
	s_lshl_b32 s0, s0, 3
	s_load_dwordx2 s[0:1], s[74:75], s0 offset:0x0
	s_add_i32 s4, s4, s5
	s_ashr_i32 s5, s4, 31
	s_lshl_b64 s[4:5], s[4:5], 12
	s_load_dword s6, s[14:15], 0x74
	s_load_dwordx2 s[10:11], s[14:15], 0x80
	s_load_dwordx2 s[12:13], s[14:15], 0x98
	s_load_dword s7, s[14:15], 0x70
	s_waitcnt lgkmcnt(0)
	s_add_u32 s0, s0, s4
	s_addc_u32 s1, s1, s5
	v_writelane_b32 v255, s0, 0
	s_bitcmp1_b32 s6, 1
	s_nop 0
	v_writelane_b32 v255, s1, 1
	v_writelane_b32 v255, s0, 2
	s_nop 1
	v_writelane_b32 v255, s1, 3
	s_cbranch_scc1 .LBB0_69
	v_writelane_b32 v255, s10, 2
	s_nop 1
	v_writelane_b32 v255, s11, 3
.LBB0_69:
	v_writelane_b32 v255, s6, 4
	s_bitcmp1_b32 s6, 3
	s_cbranch_scc1 .LBB0_71
	v_writelane_b32 v255, s12, 0
	s_nop 1
	v_writelane_b32 v255, s13, 1
.LBB0_71:
	s_mov_b32 s0, s7
	s_cmp_lt_u32 s88, 38
	s_cselect_b64 s[12:13], -1, 0
	s_and_b64 s[6:7], s[12:13], exec
	s_movk_i32 s1, 0x800
	s_cselect_b32 s80, s1, 0x1000
	s_waitcnt lgkmcnt(0)
	s_mov_b32 s1, s0
	s_cmp_lg_u32 s1, 1
	s_mov_b64 s[10:11], -1
	s_cbranch_scc0 .LBB0_362
	s_mov_b32 s1, s0
	s_cmp_lg_u32 s1, 3
	s_cbranch_scc0 .LBB0_217
	s_mov_b32 s1, s0
	s_cmp_lg_u32 s1, 4
	s_cbranch_scc0 .LBB0_128
	s_mov_b32 s1, s0
	s_cmp_lg_u32 s1, 5
	s_cbranch_scc0 .LBB0_105
	s_ashr_i32 s30, s3, 6
	s_mov_b64 s[96:97], s[14:15]
	v_and_b32_e32 v74, 63, v188
	s_cmp_lg_u32 s0, 6
	s_cbranch_scc0 .LBB0_80
	s_lshl_b32 s0, s81, 3
	s_add_i32 s0, s0, s30
	v_readlane_b32 s1, v255, 24
	s_add_i32 s0, s0, s1
	s_cmpk_gt_i32 s0, 0x1fff
	s_cbranch_scc1 .LBB0_79
	v_readlane_b32 s4, v255, 0
	v_lshlrev_b32_e32 v208, 4, v74
	v_readlane_b32 s5, v255, 1
	s_nop 4
	global_load_dwordx4 v[0:3], v208, s[4:5]
	global_load_dwordx4 v[4:7], v208, s[4:5] offset:1024
	global_load_dwordx4 v[8:11], v208, s[4:5] offset:2048
	global_load_dwordx4 v[12:15], v208, s[4:5] offset:3072
	s_lshl_b32 s10, s53, 5
	v_readlane_b32 s6, v255, 25
	s_lshr_b32 s10, s10, s6
	s_mul_i32 s6, s89, 0xd79435f
	s_mul_hi_u32 s7, s88, 0xd79435f
	s_mul_hi_u32 s5, s89, 0xd79435f
	s_add_u32 s6, s6, s7
	s_mul_i32 s4, s88, 0xd79435e5
	s_addc_u32 s5, s5, 0
	s_mul_hi_u32 s1, s88, 0xd79435e5
	s_add_u32 s4, s4, s6
	s_addc_u32 s1, s1, 0
	s_add_u32 s1, s5, s1
	s_addc_u32 s5, 0, 0
	s_mul_i32 s4, s89, 0xd79435e5
	s_mul_hi_u32 s6, s89, 0xd79435e5
	s_add_u32 s4, s4, s1
	s_addc_u32 s5, s6, s5
	s_lshl_b32 s14, s0, 2
	v_cmp_lt_i32_e32 vcc, v231, v233
	s_lshl_b64 s[4:5], s[4:5], 23
	s_ashr_i32 s15, s14, 31
	v_cndmask_b32_e32 v16, v232, v231, vcc
	v_cmp_lt_i32_e32 vcc, v253, v233
	s_and_b32 s4, s4, 0xf8000000
	v_lshlrev_b32_e32 v72, 2, v16
	v_cndmask_b32_e32 v16, v232, v253, vcc
	v_cmp_lt_i32_e32 vcc, v214, v233
	s_lshl_b64 s[0:1], s[14:15], 12
	v_readlane_b32 s11, v255, 20
	s_and_b32 s15, s14, 0xfff
	s_or_b32 s15, s15, 0x7000
	s_cmp_lg_u32 s11, 0
	s_cselect_b32 s14, s15, s14
	v_lshlrev_b32_e32 v73, 2, v16
	v_cndmask_b32_e32 v16, v232, v214, vcc
	v_cmp_lt_i32_e32 vcc, v217, v233
	s_add_u32 s0, s4, s0
	v_lshlrev_b32_e32 v75, 2, v16
	v_cndmask_b32_e32 v16, v232, v217, vcc
	v_cmp_lt_i32_e32 vcc, v238, v233
	s_addc_u32 s1, s5, s1
	v_readlane_b32 s4, v254, 7
	v_lshlrev_b32_e32 v76, 2, v16
	v_cndmask_b32_e32 v16, v232, v238, vcc
	v_cmp_lt_i32_e32 vcc, v239, v233
	v_readlane_b32 s5, v254, 8
	s_add_u32 s0, s4, s0
	v_lshlrev_b32_e32 v77, 2, v16
	v_cndmask_b32_e32 v16, v232, v239, vcc
	s_addc_u32 s1, s5, s1
	s_ashr_i32 s11, s10, 31
	v_lshlrev_b32_e32 v78, 2, v16
	v_lshl_add_u64 v[64:65], s[0:1], 0, v[208:209]
	s_lshl_b64 s[16:17], s[10:11], 12
	v_readlane_b32 s6, v254, 9
	v_readlane_b32 s7, v254, 10
